# p2a FFT prologue: removed the full vmcnt(0) between the first unit's input prefetch and the DFT-matrix fragment loads (destinations are disjoint), so the two load batches share one latency
# speedup vs baseline: 1.0088x; 1.0088x over previous
.LBB0_538:
	s_andn2_b64 vcc, exec, s[16:17]
	s_cbranch_vccnz .Lfft_arrive
	v_and_b32_e32 v83, 15, v82
	v_ashrrev_i32_e32 v87, 4, v82
	v_lshlrev_b32_e64 v110, 11, s0
	v_lshl_or_b32 v0, v83, 7, v110
	v_lshlrev_b32_e32 v111, 3, v87
	v_add_u32_e32 v0, v0, v111
	v_ashrrev_i32_e32 v2, 3, v0
	s_nop 0
	v_add_u32_e32 v4, 32, v0
	v_add_u32_e32 v10, 64, v0
	v_add_u32_e32 v0, 0x60, v0
	v_ashrrev_i32_e32 v4, 3, v4
	v_ashrrev_i32_e32 v10, 3, v10
	v_ashrrev_i32_e32 v12, 3, v0
	s_add_u32 s16, s40, 0x2610000
	v_ashrrev_i32_e32 v3, 31, v2
	v_ashrrev_i32_e32 v5, 31, v4
	s_waitcnt lgkmcnt(0)
	v_ashrrev_i32_e32 v11, 31, v10
	v_ashrrev_i32_e32 v13, 31, v12
	s_addc_u32 s17, s41, 0
	v_lshlrev_b64 v[50:51], 4, v[2:3]
	v_lshlrev_b64 v[42:43], 4, v[4:5]
	v_lshlrev_b64 v[34:35], 4, v[10:11]
	v_lshlrev_b64 v[26:27], 4, v[12:13]
	v_lshl_add_u64 v[2:3], s[16:17], 0, v[50:51]
	v_lshl_add_u64 v[6:7], s[16:17], 0, v[42:43]
	v_lshl_add_u64 v[10:11], s[16:17], 0, v[34:35]
	v_lshl_add_u64 v[14:15], s[16:17], 0, v[26:27]
	s_add_u32 s16, s40, 0x2600000
	s_addc_u32 s17, s41, 0
	s_add_u32 s20, s40, 0x2608000
	s_addc_u32 s21, s41, 0
	v_lshl_add_u64 v[28:29], s[20:21], 0, v[26:27]
	v_lshl_add_u64 v[30:31], s[16:17], 0, v[26:27]
	v_lshl_add_u64 v[36:37], s[20:21], 0, v[34:35]
	v_lshl_add_u64 v[38:39], s[16:17], 0, v[34:35]
	v_lshl_add_u64 v[44:45], s[20:21], 0, v[42:43]
	v_lshl_add_u64 v[46:47], s[16:17], 0, v[42:43]
	v_lshl_add_u64 v[52:53], s[20:21], 0, v[50:51]
	v_lshl_add_u64 v[54:55], s[16:17], 0, v[50:51]
	global_load_dwordx4 v[2:5], v[2:3], off
	s_nop 0
	global_load_dwordx4 v[6:9], v[6:7], off
	s_nop 0
	global_load_dwordx4 v[10:13], v[10:11], off
	s_nop 0
	global_load_dwordx4 v[14:17], v[14:15], off
	s_nop 0
	global_load_dwordx4 v[26:29], v[28:29], off
	s_nop 0
	global_load_dwordx4 v[30:33], v[30:31], off
	s_nop 0
	global_load_dwordx4 v[34:37], v[36:37], off
	s_nop 0
	global_load_dwordx4 v[38:41], v[38:39], off
	s_nop 0
	global_load_dwordx4 v[42:45], v[44:45], off
	s_nop 0
	global_load_dwordx4 v[46:49], v[46:47], off
	s_nop 0
	global_load_dwordx4 v[50:53], v[52:53], off
	s_nop 0
	global_load_dwordx4 v[54:57], v[54:55], off
	v_lshl_add_u32 v0, v83, 5, v111
	v_ashrrev_i32_e32 v88, 3, v0
	v_ashrrev_i32_e32 v89, 31, v88
	v_lshl_add_u64 v[88:89], v[88:89], 4, s[40:41]
	s_mov_b64 s[16:17], 0x2618000
	v_cmp_gt_i32_e32 vcc, 2, v87
	v_mov_b32_e32 v0, 0x8800
	v_bfe_u32 v105, v138, 1, 7
	v_lshlrev_b32_e32 v95, 4, v138
	v_lshl_add_u64 v[92:93], v[88:89], 0, s[16:17]
	s_mov_b64 s[16:17], 0x2618400
	v_cndmask_b32_e64 v115, v0, 0, vcc
	v_lshlrev_b32_e32 v0, 5, v105
	v_lshl_add_u64 v[96:97], v[88:89], 0, s[16:17]
	v_lshl_add_u64 v[88:89], s[42:43], 0, v[0:1]
	v_and_b32_e32 v0, 16, v95
	v_ashrrev_i32_e32 v85, 11, v138
	v_bfe_u32 v106, v138, 4, 7
	v_lshl_add_u64 v[98:99], v[88:89], 0, v[0:1]
	v_mul_i32_i24_e32 v85, 0x8800, v85
	v_mul_u32_u24_e32 v88, 0x110, v106
	v_add_u32_e32 v107, 0x200, v138
	v_add3_u32 v119, 0, v85, v88
	v_ashrrev_i32_e32 v85, 11, v107
	v_bfe_u32 v109, v107, 4, 7
	v_mul_i32_i24_e32 v85, 0x8800, v85
	v_mul_u32_u24_e32 v88, 0x110, v109
	v_add_u32_e32 v121, 0x400, v138
	v_add3_u32 v120, 0, v85, v88
	v_ashrrev_i32_e32 v85, 11, v121
	v_bfe_u32 v123, v121, 4, 7
	v_mul_i32_i24_e32 v85, 0x8800, v85
	v_mul_u32_u24_e32 v88, 0x110, v123
	v_add_u32_e32 v125, 0x600, v138
	v_add3_u32 v124, 0, v85, v88
	v_ashrrev_i32_e32 v85, 11, v125
	v_bfe_u32 v127, v125, 4, 7
	v_mul_i32_i24_e32 v85, 0x8800, v85
	v_mul_u32_u24_e32 v88, 0x110, v127
	v_add_u32_e32 v129, 0x800, v138
	v_add3_u32 v128, 0, v85, v88
	v_ashrrev_i32_e32 v85, 11, v129
	v_bfe_u32 v131, v129, 4, 7
	v_mul_i32_i24_e32 v85, 0x8800, v85
	v_mul_u32_u24_e32 v88, 0x110, v131
	v_add_u32_e32 v133, 0xa00, v138
	v_add3_u32 v132, 0, v85, v88
	v_ashrrev_i32_e32 v85, 11, v133
	v_bfe_u32 v135, v133, 4, 7
	v_mul_i32_i24_e32 v85, 0x8800, v85
	v_mul_u32_u24_e32 v88, 0x110, v135
	v_add_u32_e32 v137, 0xc00, v138
	v_add3_u32 v136, 0, v85, v88
	v_ashrrev_i32_e32 v85, 11, v137
	v_bfe_u32 v167, v137, 4, 7
	s_add_u32 s44, s40, 0x2619000
	v_mul_i32_i24_e32 v85, 0x8800, v85
	v_mul_u32_u24_e32 v88, 0x110, v167
	v_add_u32_e32 v173, 0xe00, v138
	s_addc_u32 s45, s41, 0
	v_lshlrev_b32_e32 v113, 9, v87
	v_add3_u32 v204, 0, v85, v88
	v_ashrrev_i32_e32 v85, 11, v173
	v_bfe_u32 v171, v173, 4, 7
	s_add_u32 s46, s40, 0x2639000
	v_or_b32_e32 v84, v113, v83
	v_mul_i32_i24_e32 v85, 0x8800, v85
	v_mul_u32_u24_e32 v88, 0x110, v171
	s_addc_u32 s47, s41, 0
	v_add3_u32 v205, 0, v85, v88
	v_ashrrev_i32_e32 v85, 31, v84
	v_lshl_add_u64 v[100:101], v[84:85], 3, s[46:47]
	v_ashrrev_i32_e32 v85, 3, v138
	v_and_b32_e32 v145, 0xffffff00, v85
	v_ashrrev_i32_e32 v85, 3, v107
	v_and_b32_e32 v149, 0xffffff00, v85
	v_ashrrev_i32_e32 v85, 3, v121
	v_and_b32_e32 v153, 0xffffff00, v85
	v_ashrrev_i32_e32 v85, 3, v125
	v_and_b32_e32 v157, 0xffffff00, v85
	v_lshlrev_b32_e32 v85, 3, v129
	v_lshrrev_b32_e32 v126, 4, v125
	v_and_b32_e32 v160, 0x780, v85
	v_ashrrev_i32_e32 v85, 3, v129
	v_lshlrev_b32_e64 v114, 4, s0
	v_and_b32_e32 v116, 8, v111
	v_bfe_u32 v117, v82, 2, 2
	v_lshlrev_b32_e64 v118, 5, s0
	v_bfe_u32 v154, v126, 4, 3
	v_and_b32_e32 v161, 0xffffff00, v85
	v_lshlrev_b32_e32 v85, 3, v133
	v_mul_u32_u24_e32 v126, 0x110, v83
	s_waitcnt vmcnt(0)
	v_and_b32_e32 v164, 0x780, v85
	v_ashrrev_i32_e32 v85, 3, v133
	v_add3_u32 v180, v126, v118, v111
	v_or3_b32 v111, v114, v116, v117
	s_movk_i32 s10, 0x110
	v_lshlrev_b32_e32 v82, 3, v82
	v_lshlrev_b32_e32 v91, 2, v87
	v_and_b32_e32 v165, 0xffffff00, v85
	v_lshlrev_b32_e32 v85, 3, v137
	v_mul_lo_u32 v111, v111, s10
	v_and_b32_e32 v82, 24, v82
	s_movk_i32 s10, 0x880
	v_or_b32_e32 v139, 16, v84
	v_add_lshl_u32 v141, v91, v114, 7
	v_and_b32_e32 v168, 0x780, v85
	v_ashrrev_i32_e32 v85, 3, v137
	v_add3_u32 v181, v115, v111, v82
	v_or_b32_e32 v182, 0x190, v84
	v_mul_lo_u32 v84, v87, s10
	v_mul_u32_u24_e32 v111, 0x110, v117
	v_or_b32_e32 v88, v141, v83
	v_and_b32_e32 v169, 0xffffff00, v85
	v_lshlrev_b32_e32 v85, 3, v173
	v_add3_u32 v183, v84, v111, v82
	v_add_u32_e32 v82, v110, v113
	v_lshrrev_b32_e32 v104, 4, v138
	v_lshrrev_b32_e32 v122, 4, v121
	v_ashrrev_i32_e32 v89, 31, v88
	v_and_b32_e32 v172, 0x780, v85
	v_ashrrev_i32_e32 v85, 3, v173
	v_ashrrev_i32_e32 v176, 8, v138
	v_ashrrev_i32_e32 v177, 8, v107
	v_ashrrev_i32_e32 v178, 8, v121
	v_ashrrev_i32_e32 v179, 8, v125
	v_or_b32_e32 v184, v82, v83
	v_lshlrev_b32_e32 v82, 10, v87
	v_lshlrev_b32_e32 v90, 3, v138
	v_lshrrev_b32_e32 v108, 4, v107
	v_lshrrev_b32_e32 v170, 4, v173
	v_lshl_add_u64 v[102:103], v[88:89], 3, s[44:45]
	v_bfe_u32 v142, v104, 4, 3
	v_lshlrev_b32_e32 v147, 7, v109
	v_lshlrev_b32_e32 v104, 3, v107
	v_bfe_u32 v150, v122, 4, 3
	v_and_b32_e32 v173, 0xffffff00, v85
	v_lshlrev_b32_e32 v85, 5, v176
	v_lshlrev_b32_e32 v88, 8, v105
	v_lshlrev_b32_e32 v89, 5, v177
	v_lshlrev_b32_e32 v122, 4, v107
	v_lshlrev_b32_e32 v107, 5, v178
	v_lshlrev_b32_e32 v109, 5, v179
	v_lshl_add_u32 v82, s0, 12, v82
	v_and_b32_e32 v112, 0xf0, v95
	v_and_b32_e32 v86, 0x78, v90
	v_lshrrev_b32_e32 v130, 4, v129
	v_lshrrev_b32_e32 v134, 4, v133
	v_lshrrev_b32_e32 v166, 4, v137
	v_lshlrev_b32_e32 v143, 7, v106
	v_bfe_u32 v146, v108, 4, 3
	v_lshlrev_b32_e32 v151, 7, v123
	v_lshlrev_b32_e32 v106, 3, v121
	v_lshlrev_b32_e32 v108, 3, v125
	v_add3_u32 v85, 0, v85, v88
	v_add3_u32 v89, 0, v89, v88
	v_add3_u32 v123, 0, v107, v88
	v_lshlrev_b32_e32 v121, 4, v121
	v_add3_u32 v88, 0, v109, v88
	v_lshlrev_b32_e32 v125, 4, v125
	v_lshl_or_b32 v82, v83, 1, v82
	v_or_b32_e32 v140, 16, v83
	v_and_b32_e32 v144, 0x780, v90
	v_and_b32_e32 v148, 0x780, v104
	v_and_b32_e32 v152, 0x780, v106
	v_lshlrev_b32_e32 v155, 7, v127
	v_and_b32_e32 v156, 0x780, v108
	v_bfe_u32 v158, v130, 4, 3
	v_lshlrev_b32_e32 v159, 7, v131
	v_bfe_u32 v162, v134, 4, 3
	v_lshlrev_b32_e32 v163, 7, v135
	v_bfe_u32 v166, v166, 4, 3
	v_lshlrev_b32_e32 v167, 7, v167
	v_bfe_u32 v170, v170, 4, 3
	v_lshlrev_b32_e32 v171, 7, v171
	v_or_b32_e32 v174, 0x80, v141
	v_or_b32_e32 v175, 0x180, v141
	v_ashrrev_i32_e32 v91, 31, v90
	v_ashrrev_i32_e32 v105, 31, v104
	v_ashrrev_i32_e32 v107, 31, v106
	v_ashrrev_i32_e32 v109, 31, v108
	v_add_u32_e32 v185, 0, v183
	v_add_u32_e32 v193, 0, v82
	v_add_u32_e32 v198, v119, v112
	v_add_u32_e32 v199, v120, v112
	v_add_u32_e32 v200, v124, v112
	v_add_u32_e32 v201, v128, v112
	v_add_u32_e32 v202, v132, v112
	v_add_u32_e32 v203, v136, v112
	v_add_u32_e32 v204, v204, v112
	v_add_u32_e32 v205, v205, v112
	v_lshlrev_b32_e32 v110, 1, v86
	v_add_u32_e32 v206, v85, v0
	v_add_u32_e32 v207, v89, v0
	v_add_u32_e32 v208, 0, v122
	v_add_u32_e32 v209, v123, v0
	v_add_u32_e32 v210, 0, v121
	v_add_u32_e32 v211, v88, v0
	v_add_u32_e32 v212, 0, v125
	s_branch .LBB0_541
